# row-sum adds back in the (hidden) softmax phase; only cvt_pk in PV gaps
# speedup vs baseline: 1.0998x; 1.0998x over previous
; DI void diff_core(unsigned char* smem, const u16* qptr, const u16* kbase, const u16* vtbase, int vld,
;                   int ntb, int ntw, int nvalid, int ks0, const float* lut, int qpos, bool active, bool grpB,
;                   f32x16 (&O)[4], float& l_out) {
;     ...
;     float mx = S[0][0];
; #pragma unroll
;     for (int kb = 0; kb < 2; ++kb)
; #pragma unroll
;       for (int i = 0; i < 16; ++i) mx = fmaxf(mx, S[kb][i]);
;     {
;       const unsigned um = __float_as_uint(mx);
;       const auto sw = __builtin_amdgcn_permlane32_swap(um, um, false, false);
;       mx = fmaxf(__uint_as_float(sw[0]), __uint_as_float(sw[1]));
;     }
;     if (t == 0) {
;       m = mx;
; #pragma unroll
;       for (int kb = 0; kb < 2; ++kb)
; #pragma unroll
;         for (int i = 0; i < 16; ++i) S[kb][i] -= mx;
;     } else if (__any(mx > 8.f)) {
;       const float d = fmaxf(mx, 0.f);
;       const float alpha = __builtin_amdgcn_exp2f(-d);
;       m += d;
;       l *= alpha;
; #pragma unroll
;       for (int tt = 0; tt < 4; ++tt)
; #pragma unroll
;         for (int e = 0; e < 16; ++e) O[tt][e] *= alpha;
; #pragma unroll
;       for (int kb = 0; kb < 2; ++kb)
; #pragma unroll
;         for (int i = 0; i < 16; ++i) S[kb][i] -= d;
;     }
;     float ps = 0.f;
; #pragma unroll
;     for (int kb = 0; kb < 2; ++kb)
; #pragma unroll
;       for (int i = 0; i < 16; ++i) {
;         const float pe = __builtin_amdgcn_exp2f(S[kb][i]);
;         S[kb][i] = pe;
;         ps += pe;
;       }
;     l += ps;
; #pragma unroll
;     for (int kb = 0; kb < 2; ++kb)
; #pragma unroll
;       for (int s2 = 0; s2 < 2; ++s2) {
;         u32x4 pk;
;         pk.x = pack2(S[kb][8 * s2 + 0], S[kb][8 * s2 + 1]);
;         pk.y = pack2(S[kb][8 * s2 + 2], S[kb][8 * s2 + 3]);
;         pk.z = pack2(S[kb][8 * s2 + 4], S[kb][8 * s2 + 5]);
;         pk.w = pack2(S[kb][8 * s2 + 6], S[kb][8 * s2 + 7]);
;         P[kb * 2 + s2] = pk;
;       }
.LBB0_357:
	v_max_f32_e32 v32, v1, v1
	v_max_f32_e32 v33, v0, v0
	v_max_f32_e32 v32, v33, v32
	v_max3_f32 v32, v32, v2, v3
	v_max3_f32 v32, v32, v4, v5
	v_max3_f32 v32, v32, v6, v7
	v_max3_f32 v32, v32, v8, v9
	v_max3_f32 v32, v32, v10, v11
	v_max3_f32 v32, v32, v12, v13
	v_max3_f32 v32, v32, v14, v15
	v_max3_f32 v32, v32, v16, v17
	v_max3_f32 v32, v32, v18, v19
	v_max3_f32 v32, v32, v20, v21
	v_max3_f32 v32, v32, v22, v23
	v_max3_f32 v32, v32, v24, v25
	v_max3_f32 v32, v32, v26, v27
	v_max3_f32 v32, v32, v28, v29
	v_max3_f32 v32, v32, v30, v31
	v_mov_b32_e32 v33, v32
	s_nop 1
	v_permlane32_swap_b32_e32 v32, v33
	v_max_f32_e32 v33, v33, v33
	v_max_f32_e32 v32, v32, v32
	v_max_f32_e32 v191, v32, v33
	v_xor_b32_e32 v232, 0x80000000, v191
	v_mov_b32_e32 v233, v232
	v_mov_b32_e32 v234, v232
	v_mov_b32_e32 v235, v232
	v_mov_b32_e32 v236, v232
	v_mov_b32_e32 v237, v232
	v_mov_b32_e32 v238, v232
	v_mov_b32_e32 v239, v232
	v_mov_b32_e32 v240, v232
	v_mov_b32_e32 v241, v232
	v_mov_b32_e32 v242, v232
	v_mov_b32_e32 v243, v232
	v_mov_b32_e32 v244, v232
	v_mov_b32_e32 v245, v232
	v_mov_b32_e32 v246, v232
	v_mov_b32_e32 v247, v232
	v_sub_f32_e32 v0, v0, v191
	v_sub_f32_e32 v1, v1, v191
	v_exp_f32_e32 v96, v0
	v_sub_f32_e32 v2, v2, v191
	v_exp_f32_e32 v97, v1
	v_sub_f32_e32 v3, v3, v191
	v_exp_f32_e32 v98, v2
	v_sub_f32_e32 v4, v4, v191
	v_exp_f32_e32 v99, v3
	v_sub_f32_e32 v5, v5, v191
	v_exp_f32_e32 v100, v4
	v_sub_f32_e32 v6, v6, v191
	v_exp_f32_e32 v101, v5
	v_sub_f32_e32 v7, v7, v191
	v_exp_f32_e32 v102, v6
	v_sub_f32_e32 v8, v8, v191
	v_exp_f32_e32 v103, v7
	v_sub_f32_e32 v9, v9, v191
	v_exp_f32_e32 v104, v8
	v_sub_f32_e32 v10, v10, v191
	v_exp_f32_e32 v105, v9
	v_sub_f32_e32 v11, v11, v191
	v_exp_f32_e32 v106, v10
	v_sub_f32_e32 v12, v12, v191
	v_exp_f32_e32 v107, v11
	v_sub_f32_e32 v13, v13, v191
	v_exp_f32_e32 v108, v12
	v_sub_f32_e32 v14, v14, v191
	v_exp_f32_e32 v109, v13
	v_sub_f32_e32 v15, v15, v191
	v_exp_f32_e32 v110, v14
	v_sub_f32_e32 v16, v16, v191
	v_exp_f32_e32 v111, v15
	v_sub_f32_e32 v17, v17, v191
	v_exp_f32_e32 v112, v16
	v_sub_f32_e32 v18, v18, v191
	v_exp_f32_e32 v113, v17
	v_sub_f32_e32 v19, v19, v191
	v_exp_f32_e32 v114, v18
	v_sub_f32_e32 v20, v20, v191
	v_exp_f32_e32 v115, v19
	v_sub_f32_e32 v21, v21, v191
	v_exp_f32_e32 v116, v20
	v_sub_f32_e32 v22, v22, v191
	v_exp_f32_e32 v117, v21
	v_sub_f32_e32 v23, v23, v191
	v_exp_f32_e32 v118, v22
	v_sub_f32_e32 v24, v24, v191
	v_exp_f32_e32 v119, v23
	v_sub_f32_e32 v25, v25, v191
	v_exp_f32_e32 v120, v24
	v_sub_f32_e32 v26, v26, v191
	v_exp_f32_e32 v121, v25
	v_sub_f32_e32 v27, v27, v191
	v_exp_f32_e32 v122, v26
	v_sub_f32_e32 v28, v28, v191
	v_exp_f32_e32 v123, v27
	v_sub_f32_e32 v29, v29, v191
	v_exp_f32_e32 v124, v28
	v_sub_f32_e32 v30, v30, v191
	v_exp_f32_e32 v125, v29
	v_sub_f32_e32 v31, v31, v191
	v_exp_f32_e32 v126, v30
	v_exp_f32_e32 v127, v31
	s_lshl_b32 s0, s62, 1
	s_sub_i32 s63, 0, s0
	s_lshl_b32 s0, s59, 10
	s_lshl_b32 s1, s62, 9
	s_add_i32 s0, s0, s1
	v_mov_b32_e32 v181, 0
	v_or_b32_e32 v0, s0, v183
	v_lshlrev_b32_e32 v1, 2, v182
	v_sub_u32_e32 v0, v0, v1
	s_lshl_b32 s0, s39, 7
	v_subrev_u32_e32 v0, s0, v0
	v_mov_b32_e32 v14, v163
	v_mov_b32_e32 v15, v163
	v_add_u32_e32 v199, s38, v0
	v_mov_b32_e32 v0, v163
	v_mov_b32_e32 v1, v163
	v_mov_b32_e32 v2, v163
	v_mov_b32_e32 v3, v163
	v_mov_b32_e32 v4, v163
	v_mov_b32_e32 v5, v163
	v_mov_b32_e32 v6, v163
	v_mov_b32_e32 v7, v163
	v_mov_b32_e32 v8, v163
	v_mov_b32_e32 v9, v163
	v_mov_b32_e32 v10, v163
	v_mov_b32_e32 v11, v163
	v_mov_b32_e32 v12, v163
	v_mov_b32_e32 v13, v163
	v_mov_b64_e32 v[30:31], v[14:15]
	v_mov_b64_e32 v[46:47], v[14:15]
	v_mov_b64_e32 v[62:63], v[14:15]
	v_add_u32_e32 v195, v188, v184
	v_add_u32_e32 v196, v187, v184
	v_add_u32_e32 v197, v186, v184
	v_add_u32_e32 v198, v185, v184
	s_movk_i32 s64, 0xff00
	s_mov_b32 s65, 0x20000
	v_mov_b64_e32 v[28:29], v[12:13]
	v_mov_b64_e32 v[26:27], v[10:11]
	v_mov_b64_e32 v[24:25], v[8:9]
	v_mov_b64_e32 v[22:23], v[6:7]
	v_mov_b64_e32 v[20:21], v[4:5]
	v_mov_b64_e32 v[18:19], v[2:3]
	v_mov_b64_e32 v[16:17], v[0:1]
	v_mov_b64_e32 v[44:45], v[12:13]
	v_mov_b64_e32 v[42:43], v[10:11]
	v_mov_b64_e32 v[40:41], v[8:9]
	v_mov_b64_e32 v[38:39], v[6:7]
	v_mov_b64_e32 v[36:37], v[4:5]
	v_mov_b64_e32 v[34:35], v[2:3]
	v_mov_b64_e32 v[32:33], v[0:1]
	v_mov_b64_e32 v[60:61], v[12:13]
	v_mov_b64_e32 v[58:59], v[10:11]
	v_mov_b64_e32 v[56:57], v[8:9]
	v_mov_b64_e32 v[54:55], v[6:7]
	v_mov_b64_e32 v[52:53], v[4:5]
	v_mov_b64_e32 v[50:51], v[2:3]
	v_mov_b64_e32 v[48:49], v[0:1]
	v_add_f32_e32 v250, v97, v96
	v_add_f32_e32 v250, v98, v250
	v_add_f32_e32 v250, v99, v250
	v_add_f32_e32 v250, v100, v250
	v_add_f32_e32 v250, v101, v250
	v_add_f32_e32 v250, v102, v250
	v_add_f32_e32 v250, v103, v250
	v_add_f32_e32 v250, v104, v250
	v_add_f32_e32 v250, v105, v250
	v_add_f32_e32 v250, v106, v250
	v_add_f32_e32 v250, v107, v250
	v_add_f32_e32 v250, v108, v250
	v_add_f32_e32 v250, v109, v250
	v_add_f32_e32 v250, v110, v250
	v_add_f32_e32 v250, v111, v250
	v_add_f32_e32 v250, v112, v250
	v_add_f32_e32 v250, v113, v250
	v_add_f32_e32 v250, v114, v250
	v_add_f32_e32 v250, v115, v250
	v_add_f32_e32 v250, v116, v250
	v_add_f32_e32 v250, v117, v250
	v_add_f32_e32 v250, v118, v250
	v_add_f32_e32 v250, v119, v250
	v_add_f32_e32 v250, v120, v250
	v_add_f32_e32 v250, v121, v250
	v_add_f32_e32 v250, v122, v250
	v_add_f32_e32 v250, v123, v250
	v_add_f32_e32 v250, v124, v250
	v_add_f32_e32 v250, v125, v250
	v_add_f32_e32 v250, v126, v250
	v_add_f32_e32 v250, v127, v250
	v_add_f32_e32 v181, v181, v250
	s_mov_b32 s0, 0
	v_add_u32_e32 v248, s0, v195
	ds_read_b128 v[200:203], v248 offset:16384
	ds_read_b128 v[204:207], v248 offset:20480
	ds_read_b128 v[208:211], v248 offset:24576
	ds_read_b128 v[212:215], v248 offset:28672
	v_add_u32_e32 v249, s0, v196
	ds_read_b128 v[216:219], v249 offset:16384
	ds_read_b128 v[220:223], v249 offset:20480
	ds_read_b128 v[224:227], v249 offset:24576
	ds_read_b128 v[228:231], v249 offset:28672
	s_branch .LBB0_360
; DI void diff_core(unsigned char* smem, const u16* qptr, const u16* kbase, const u16* vtbase, int vld,
;                   int ntb, int ntw, int nvalid, int ks0, const float* lut, int qpos, bool active, bool grpB,
;                   f32x16 (&O)[4], float& l_out) {
;     ...
;     float ps = 0.f;
; #pragma unroll
;     for (int kb = 0; kb < 2; ++kb)
; #pragma unroll
;       for (int i = 0; i < 16; ++i) {
;         const float pe = __builtin_amdgcn_exp2f(S[kb][i]);
;         S[kb][i] = pe;
;         ps += pe;
;       }
;     l += ps;
.LBB0_358:
	v_exp_f32_e32 v96, v96
	v_exp_f32_e32 v97, v97
	v_exp_f32_e32 v98, v98
	v_exp_f32_e32 v99, v99
	v_exp_f32_e32 v100, v100
	v_exp_f32_e32 v101, v101
	v_exp_f32_e32 v102, v102
	v_exp_f32_e32 v103, v103
	v_exp_f32_e32 v104, v104
	v_exp_f32_e32 v105, v105
	v_exp_f32_e32 v106, v106
	v_exp_f32_e32 v107, v107
	v_exp_f32_e32 v108, v108
	v_exp_f32_e32 v109, v109
	v_exp_f32_e32 v110, v110
	v_exp_f32_e32 v111, v111
	v_exp_f32_e32 v112, v112
	v_exp_f32_e32 v113, v113
	v_exp_f32_e32 v114, v114
	v_exp_f32_e32 v115, v115
	v_exp_f32_e32 v116, v116
	v_exp_f32_e32 v117, v117
	v_exp_f32_e32 v118, v118
	v_exp_f32_e32 v119, v119
	v_exp_f32_e32 v120, v120
	v_exp_f32_e32 v121, v121
	v_exp_f32_e32 v122, v122
	v_exp_f32_e32 v123, v123
	v_exp_f32_e32 v124, v124
	v_exp_f32_e32 v125, v125
	v_exp_f32_e32 v126, v126
	v_exp_f32_e32 v127, v127
	v_add_f32_e32 v250, v97, v96
	v_add_f32_e32 v250, v98, v250
	v_add_f32_e32 v250, v99, v250
	v_add_f32_e32 v250, v100, v250
	v_add_f32_e32 v250, v101, v250
	v_add_f32_e32 v250, v102, v250
	v_add_f32_e32 v250, v103, v250
	v_add_f32_e32 v250, v104, v250
	v_add_f32_e32 v250, v105, v250
	v_add_f32_e32 v250, v106, v250
	v_add_f32_e32 v250, v107, v250
	v_add_f32_e32 v250, v108, v250
	v_add_f32_e32 v250, v109, v250
	v_add_f32_e32 v250, v110, v250
	v_add_f32_e32 v250, v111, v250
	v_add_f32_e32 v250, v112, v250
	v_add_f32_e32 v250, v113, v250
	v_add_f32_e32 v250, v114, v250
	v_add_f32_e32 v250, v115, v250
	v_add_f32_e32 v250, v116, v250
	v_add_f32_e32 v250, v117, v250
	v_add_f32_e32 v250, v118, v250
	v_add_f32_e32 v250, v119, v250
	v_add_f32_e32 v250, v120, v250
	v_add_f32_e32 v250, v121, v250
	v_add_f32_e32 v250, v122, v250
	v_add_f32_e32 v250, v123, v250
	v_add_f32_e32 v250, v124, v250
	v_add_f32_e32 v250, v125, v250
	v_add_f32_e32 v250, v126, v250
	v_add_f32_e32 v250, v127, v250
	v_add_f32_e32 v181, v181, v250
	s_add_i32 s0, s65, 0x8000
	s_and_b32 s0, s0, 0x18000
	v_add_u32_e32 v248, s0, v195
	ds_read_b128 v[200:203], v248 offset:16384
	ds_read_b128 v[204:207], v248 offset:20480
	ds_read_b128 v[208:211], v248 offset:24576
	ds_read_b128 v[212:215], v248 offset:28672
	v_add_u32_e32 v249, s0, v196
	ds_read_b128 v[216:219], v249 offset:16384
	ds_read_b128 v[220:223], v249 offset:20480
	ds_read_b128 v[224:227], v249 offset:24576
	ds_read_b128 v[228:231], v249 offset:28672

; DI void diff_core(unsigned char* smem, const u16* qptr, const u16* kbase, const u16* vtbase, int vld,
;                   int ntb, int ntw, int nvalid, int ks0, const float* lut, int qpos, bool active, bool grpB,
;                   f32x16 (&O)[4], float& l_out) {
;     ...
;   auto pv = [&](int slot) {
;     if (grpB) __builtin_amdgcn_s_setprio(2); else __builtin_amdgcn_s_setprio(1);
;     const LAS unsigned char* b = lds + slot * D_SLOT;
;     bf16x8 va[4], vb[4];
; #pragma unroll
;     for (int tt = 0; tt < 4; ++tt) va[tt] = *reinterpret_cast<const LAS bf16x8*>(b + voff[0] + tt * 32 * 128);
; #pragma unroll
;     for (int tt = 0; tt < 4; ++tt) vb[tt] = *reinterpret_cast<const LAS bf16x8*>(b + voff[1] + tt * 32 * 128);
;     {
;       const bf16x8 pf = __builtin_bit_cast(bf16x8, P[0]);
; #pragma unroll
;       for (int tt = 0; tt < 4; ++tt) O[tt] = MFMA(va[tt], pf, O[tt]);
;     }
; #pragma unroll
;     for (int tt = 0; tt < 4; ++tt) va[tt] = *reinterpret_cast<const LAS bf16x8*>(b + voff[2] + tt * 32 * 128);
;     {
;       const bf16x8 pf = __builtin_bit_cast(bf16x8, P[1]);
; #pragma unroll
;       for (int tt = 0; tt < 4; ++tt) O[tt] = MFMA(vb[tt], pf, O[tt]);
;     }
; #pragma unroll
;     for (int tt = 0; tt < 4; ++tt) vb[tt] = *reinterpret_cast<const LAS bf16x8*>(b + voff[3] + tt * 32 * 128);
;     {
;       const bf16x8 pf = __builtin_bit_cast(bf16x8, P[2]);
; #pragma unroll
;       for (int tt = 0; tt < 4; ++tt) O[tt] = MFMA(va[tt], pf, O[tt]);
;     }
;     {
;       const bf16x8 pf = __builtin_bit_cast(bf16x8, P[3]);
; #pragma unroll
;       for (int tt = 0; tt < 4; ++tt) O[tt] = MFMA(vb[tt], pf, O[tt]);
;     }
;     __builtin_amdgcn_sched_group_barrier(0x100, 8, 0);
;     __builtin_amdgcn_sched_group_barrier(0x008, 4, 0);
;     __builtin_amdgcn_sched_group_barrier(0x100, 4, 0);
;     __builtin_amdgcn_sched_group_barrier(0x008, 4, 0);
;     __builtin_amdgcn_sched_group_barrier(0x100, 4, 0);
;     __builtin_amdgcn_sched_group_barrier(0x008, 8, 0);
;     __builtin_amdgcn_s_setprio(0);
;   };
;     ...
;     for (int kb = 0; kb < 2; ++kb)
; #pragma unroll
;       for (int s2 = 0; s2 < 2; ++s2) {
;         u32x4 pk;
;         pk.x = pack2(S[kb][8 * s2 + 0], S[kb][8 * s2 + 1]);
;         pk.y = pack2(S[kb][8 * s2 + 2], S[kb][8 * s2 + 3]);
;         pk.z = pack2(S[kb][8 * s2 + 4], S[kb][8 * s2 + 5]);
;         pk.w = pack2(S[kb][8 * s2 + 6], S[kb][8 * s2 + 7]);
.LBB0_360:
	s_add_i32 s66, s64, 0x101
	s_cmp_gt_u32 s66, s16
	s_cbranch_scc1 .LBB0_362
	s_setprio 2
	s_and_b32 s0, s65, 0x18000
	v_add_u32_e32 v248, s0, v197
	ds_read_b128 v[64:67], v248 offset:16384
	ds_read_b128 v[68:71], v248 offset:20480
	ds_read_b128 v[72:75], v248 offset:24576
	ds_read_b128 v[76:79], v248 offset:28672
	s_add_i32 s67, s65, 0xfffe8000
	s_and_b32 s67, s67, 0x18000
	v_cvt_pk_bf16_f32 v144, v96, v97
	v_cvt_pk_bf16_f32 v145, v98, v99
	v_cvt_pk_bf16_f32 v146, v100, v101
	v_cvt_pk_bf16_f32 v147, v102, v103
	s_nop 0
	s_waitcnt lgkmcnt(4)
	v_mfma_f32_32x32x16_bf16 v[48:63], v[200:203], v[144:147], v[48:63]
	v_cvt_pk_bf16_f32 v148, v104, v105
	v_cvt_pk_bf16_f32 v149, v106, v107
	v_add_u32_e32 v249, s0, v198
	ds_read_b128 v[80:83], v249 offset:16384
	ds_read_b128 v[84:87], v249 offset:20480
	ds_read_b128 v[88:91], v249 offset:24576
	ds_read_b128 v[92:95], v249 offset:28672
	v_mfma_f32_32x32x16_bf16 v[32:47], v[204:207], v[144:147], v[32:47]
	v_cvt_pk_bf16_f32 v150, v108, v109
	v_cvt_pk_bf16_f32 v151, v110, v111
	v_mfma_f32_32x32x16_bf16 v[16:31], v[208:211], v[144:147], v[16:31]
	v_mfma_f32_32x32x16_bf16 v[0:15], v[212:215], v[144:147], v[0:15]
	v_mfma_f32_32x32x16_bf16 v[48:63], v[216:219], v[148:151], v[48:63]
	v_cvt_pk_bf16_f32 v152, v112, v113
	v_cvt_pk_bf16_f32 v153, v114, v115
	v_mfma_f32_32x32x16_bf16 v[32:47], v[220:223], v[148:151], v[32:47]
	v_cvt_pk_bf16_f32 v154, v116, v117
	v_cvt_pk_bf16_f32 v155, v118, v119
	v_mfma_f32_32x32x16_bf16 v[16:31], v[224:227], v[148:151], v[16:31]
	v_mfma_f32_32x32x16_bf16 v[0:15], v[228:231], v[148:151], v[0:15]
	v_add_u32_e32 v248, s67, v177
	ds_read_b128 v[200:203], v248
	ds_read_b128 v[204:207], v248 offset:8192
	v_add_u32_e32 v249, s67, v178
	ds_read_b128 v[208:211], v249
	ds_read_b128 v[212:215], v249 offset:8192
	s_waitcnt lgkmcnt(8)
	v_mfma_f32_32x32x16_bf16 v[48:63], v[64:67], v[152:155], v[48:63]
	v_cvt_pk_bf16_f32 v156, v120, v121
	v_cvt_pk_bf16_f32 v157, v122, v123
	v_mfma_f32_32x32x16_bf16 v[32:47], v[68:71], v[152:155], v[32:47]
	v_cvt_pk_bf16_f32 v158, v124, v125
	v_cvt_pk_bf16_f32 v159, v126, v127
	v_mfma_f32_32x32x16_bf16 v[16:31], v[72:75], v[152:155], v[16:31]
	v_mfma_f32_32x32x16_bf16 v[0:15], v[76:79], v[152:155], v[0:15]
	v_add_u32_e32 v248, s67, v179
	ds_read_b128 v[216:219], v248
	ds_read_b128 v[220:223], v248 offset:8192
	v_add_u32_e32 v249, s67, v180
	ds_read_b128 v[224:227], v249
	ds_read_b128 v[228:231], v249 offset:8192
	s_waitcnt lgkmcnt(8)
	v_mfma_f32_32x32x16_bf16 v[48:63], v[80:83], v[156:159], v[48:63]
	v_mfma_f32_32x32x16_bf16 v[32:47], v[84:87], v[156:159], v[32:47]
	v_mfma_f32_32x32x16_bf16 v[16:31], v[88:91], v[156:159], v[16:31]
	v_mfma_f32_32x32x16_bf16 v[0:15], v[92:95], v[156:159], v[0:15]
	s_setprio 0

; DI void diff_core(unsigned char* smem, const u16* qptr, const u16* kbase, const u16* vtbase, int vld,
;                   int ntb, int ntw, int nvalid, int ks0, const float* lut, int qpos, bool active, bool grpB,
;                   f32x16 (&O)[4], float& l_out) {
;     ...
;   auto pv = [&](int slot) {
;     if (grpB) __builtin_amdgcn_s_setprio(2); else __builtin_amdgcn_s_setprio(1);
;     const LAS unsigned char* b = lds + slot * D_SLOT;
;     bf16x8 va[4], vb[4];
; #pragma unroll
;     for (int tt = 0; tt < 4; ++tt) va[tt] = *reinterpret_cast<const LAS bf16x8*>(b + voff[0] + tt * 32 * 128);
; #pragma unroll
;     for (int tt = 0; tt < 4; ++tt) vb[tt] = *reinterpret_cast<const LAS bf16x8*>(b + voff[1] + tt * 32 * 128);
;     {
;       const bf16x8 pf = __builtin_bit_cast(bf16x8, P[0]);
; #pragma unroll
;       for (int tt = 0; tt < 4; ++tt) O[tt] = MFMA(va[tt], pf, O[tt]);
;     }
; #pragma unroll
;     for (int tt = 0; tt < 4; ++tt) va[tt] = *reinterpret_cast<const LAS bf16x8*>(b + voff[2] + tt * 32 * 128);
;     {
;       const bf16x8 pf = __builtin_bit_cast(bf16x8, P[1]);
; #pragma unroll
;       for (int tt = 0; tt < 4; ++tt) O[tt] = MFMA(vb[tt], pf, O[tt]);
;     }
; #pragma unroll
;     for (int tt = 0; tt < 4; ++tt) vb[tt] = *reinterpret_cast<const LAS bf16x8*>(b + voff[3] + tt * 32 * 128);
;     {
;       const bf16x8 pf = __builtin_bit_cast(bf16x8, P[2]);
; #pragma unroll
;       for (int tt = 0; tt < 4; ++tt) O[tt] = MFMA(va[tt], pf, O[tt]);
;     }
;     {
;       const bf16x8 pf = __builtin_bit_cast(bf16x8, P[3]);
; #pragma unroll
;       for (int tt = 0; tt < 4; ++tt) O[tt] = MFMA(vb[tt], pf, O[tt]);
;     }
;     __builtin_amdgcn_sched_group_barrier(0x100, 8, 0);
;     ...
;     float ps = 0.f;
; #pragma unroll
;     for (int kb = 0; kb < 2; ++kb)
; #pragma unroll
;       for (int i = 0; i < 16; ++i) {
;         const float pe = __builtin_amdgcn_exp2f(S[kb][i]);
;         S[kb][i] = pe;
;         ps += pe;
;       }
;     l += ps;
; #pragma unroll
;     for (int kb = 0; kb < 2; ++kb)
; #pragma unroll
;       for (int s2 = 0; s2 < 2; ++s2) {
;         u32x4 pk;
;         pk.x = pack2(S[kb][8 * s2 + 0], S[kb][8 * s2 + 1]);
;         pk.y = pack2(S[kb][8 * s2 + 2], S[kb][8 * s2 + 3]);
;         pk.z = pack2(S[kb][8 * s2 + 4], S[kb][8 * s2 + 5]);
;         pk.w = pack2(S[kb][8 * s2 + 6], S[kb][8 * s2 + 7]);
;         P[kb * 2 + s2] = pk;
;       }
.LBB0_383:
	v_exp_f32_e32 v80, v80
	v_exp_f32_e32 v81, v81
	v_exp_f32_e32 v82, v82
	v_exp_f32_e32 v83, v83
	v_exp_f32_e32 v84, v84
	v_exp_f32_e32 v85, v85
	v_exp_f32_e32 v86, v86
	v_exp_f32_e32 v87, v87
	v_exp_f32_e32 v88, v88
	v_exp_f32_e32 v89, v89
	v_exp_f32_e32 v90, v90
	v_exp_f32_e32 v91, v91
	v_exp_f32_e32 v92, v92
	v_exp_f32_e32 v93, v93
	v_exp_f32_e32 v94, v94
	v_exp_f32_e32 v95, v95
	v_exp_f32_e32 v64, v64
	v_exp_f32_e32 v65, v65
	v_exp_f32_e32 v66, v66
	v_exp_f32_e32 v67, v67
	v_exp_f32_e32 v68, v68
	v_exp_f32_e32 v69, v69
	v_exp_f32_e32 v70, v70
	v_exp_f32_e32 v71, v71
	v_exp_f32_e32 v72, v72
	v_exp_f32_e32 v73, v73
	v_exp_f32_e32 v74, v74
	v_exp_f32_e32 v75, v75
	v_exp_f32_e32 v76, v76
	v_exp_f32_e32 v77, v77
	v_exp_f32_e32 v78, v78
	v_exp_f32_e32 v79, v79
	v_add_f32_e32 v250, v81, v80
	v_add_f32_e32 v250, v82, v250
	v_add_f32_e32 v250, v83, v250
	v_add_f32_e32 v250, v84, v250
	v_add_f32_e32 v250, v85, v250
	v_add_f32_e32 v250, v86, v250
	v_add_f32_e32 v250, v87, v250
	v_add_f32_e32 v250, v88, v250
	v_add_f32_e32 v250, v89, v250
	v_add_f32_e32 v250, v90, v250
	v_add_f32_e32 v250, v91, v250
	v_add_f32_e32 v250, v92, v250
	v_add_f32_e32 v250, v93, v250
	v_add_f32_e32 v250, v94, v250
	v_add_f32_e32 v250, v95, v250
	v_add_f32_e32 v250, v64, v250
	v_add_f32_e32 v250, v65, v250
	v_add_f32_e32 v250, v66, v250
	v_add_f32_e32 v250, v67, v250
	v_add_f32_e32 v250, v68, v250
	v_add_f32_e32 v250, v69, v250
	v_add_f32_e32 v250, v70, v250
	v_add_f32_e32 v250, v71, v250
	v_add_f32_e32 v250, v72, v250
	v_add_f32_e32 v250, v73, v250
	v_add_f32_e32 v250, v74, v250
	v_add_f32_e32 v250, v75, v250
	v_add_f32_e32 v250, v76, v250
	v_add_f32_e32 v250, v77, v250
	v_add_f32_e32 v250, v78, v250
	v_add_f32_e32 v250, v79, v250
	v_add_f32_e32 v181, v181, v250
	v_cvt_pk_bf16_f32 v144, v80, v81
	v_cvt_pk_bf16_f32 v145, v82, v83
	v_cvt_pk_bf16_f32 v146, v84, v85
	v_cvt_pk_bf16_f32 v147, v86, v87
.LBB0_384:
	s_waitcnt vmcnt(4)
	s_barrier
	s_andn2_b64 vcc, exec, s[0:1]
	s_cbranch_vccnz .LBB0_386
	s_setprio 2
	s_waitcnt lgkmcnt(0)
	v_mfma_f32_32x32x16_bf16 v[48:63], v[200:203], v[144:147], v[48:63]
	v_cvt_pk_bf16_f32 v148, v88, v89
	v_cvt_pk_bf16_f32 v149, v90, v91
	v_add_u32_e32 v97, s100, v186
	ds_read_b128 v[98:101], v97 offset:16384
	ds_read_b128 v[102:105], v97 offset:20480
	ds_read_b128 v[106:109], v97 offset:24576
	ds_read_b128 v[110:113], v97 offset:28672
	v_mfma_f32_32x32x16_bf16 v[32:47], v[204:207], v[144:147], v[32:47]
	v_cvt_pk_bf16_f32 v150, v92, v93
	v_cvt_pk_bf16_f32 v151, v94, v95
	v_add_u32_e32 v126, s100, v184
	ds_read_b128 v[114:117], v126 offset:16384
	ds_read_b128 v[118:121], v126 offset:20480
	ds_read_b128 v[122:125], v126 offset:24576
	ds_read_b128 v[196:199], v126 offset:28672
	v_mfma_f32_32x32x16_bf16 v[16:31], v[208:211], v[144:147], v[16:31]
	v_mfma_f32_32x32x16_bf16 v[0:15], v[212:215], v[144:147], v[0:15]
	v_mfma_f32_32x32x16_bf16 v[48:63], v[216:219], v[148:151], v[48:63]
	v_cvt_pk_bf16_f32 v152, v64, v65
	v_cvt_pk_bf16_f32 v153, v66, v67
	v_mfma_f32_32x32x16_bf16 v[32:47], v[220:223], v[148:151], v[32:47]
	v_cvt_pk_bf16_f32 v154, v68, v69
	v_cvt_pk_bf16_f32 v155, v70, v71
	v_mfma_f32_32x32x16_bf16 v[16:31], v[224:227], v[148:151], v[16:31]
	v_mfma_f32_32x32x16_bf16 v[0:15], v[228:231], v[148:151], v[0:15]
	v_add_u32_e32 v97, s101, v177
	ds_read_b128 v[200:203], v97
	ds_read_b128 v[204:207], v97 offset:8192
	v_add_u32_e32 v126, s101, v178
	ds_read_b128 v[208:211], v126
	ds_read_b128 v[212:215], v126 offset:8192
	s_waitcnt lgkmcnt(8)
	v_mfma_f32_32x32x16_bf16 v[48:63], v[98:101], v[152:155], v[48:63]
	v_cvt_pk_bf16_f32 v156, v72, v73
	v_cvt_pk_bf16_f32 v157, v74, v75
	v_mfma_f32_32x32x16_bf16 v[32:47], v[102:105], v[152:155], v[32:47]
	v_cvt_pk_bf16_f32 v158, v76, v77
	v_cvt_pk_bf16_f32 v159, v78, v79
	v_mfma_f32_32x32x16_bf16 v[16:31], v[106:109], v[152:155], v[16:31]
	v_mfma_f32_32x32x16_bf16 v[0:15], v[110:113], v[152:155], v[0:15]
	v_add_u32_e32 v97, s101, v179
	ds_read_b128 v[216:219], v97
	ds_read_b128 v[220:223], v97 offset:8192
	v_add_u32_e32 v126, s101, v180
	ds_read_b128 v[224:227], v126
	ds_read_b128 v[228:231], v126 offset:8192
	s_waitcnt lgkmcnt(8)
	v_mfma_f32_32x32x16_bf16 v[48:63], v[114:117], v[156:159], v[48:63]
	v_mfma_f32_32x32x16_bf16 v[32:47], v[118:121], v[156:159], v[32:47]
	v_mfma_f32_32x32x16_bf16 v[16:31], v[122:125], v[156:159], v[16:31]
	v_mfma_f32_32x32x16_bf16 v[0:15], v[196:199], v[156:159], v[0:15]
	s_setprio 0
